# scan loops: RWKV v-address add hoisted to the back edge and last v_mov copy replaced by op_sel; HGRN second write address folded into a ds_write offset
# baseline (speedup 1.0000x reference)
; #define HG_LD(X, tl_) do { const float* f_ = sF + (tl_) * 128 + seg * 4; const float* q_ = sQ + (tl_) * 128 + seg * 4;   \
;                 X##f0 = *(const f32x4*)(f_); X##f1 = *(const f32x4*)(f_ + 64); X##q0 = *(const f32x4*)(q_); X##q1 = *(const f32x4*)(q_ + 64); \
;                 X##va = sDV[(tl_) * 64 + cp]; X##vb = sDV[(tl_) * 64 + 32 + cp]; } while (0)
; __device__ __forceinline__ void phase_hgrn(KP P, int l_, unsigned char* shm) {
;     ...
;             {
;                 f32x4 Af0, Af1, Aq0, Aq1; float Ava, Avb;
;                 f32x4 Bf0, Bf1, Bq0, Bq1; float Bva, Bvb;
;                 HG_LD(A, 0);
; #pragma unroll 2
;                 for (int tl = 0; tl < T; tl += 2) {
;                     HG_LD(B, tl + 1);
;                     HG_STEP(A, tl);
;                     HG_LD(A, tl + 2);
;                     HG_STEP(B, tl + 1);
;                 }
.LBB0_2162:
	ds_read_b128 v[18:21], v111
	ds_read_b128 v[14:17], v111 offset:256
	ds_read_b128 v[10:13], v111 offset:16384
	ds_read_b128 v[6:9], v111 offset:16640
	ds_read2_b32 v[78:79], v116 offset1:32
	s_mov_b32 s17, -2
	v_mov_b32_e32 v129, v110
	v_mov_b32_e32 v130, v109
	v_and_b32_e32 v133, 3, v228
	v_mul_u32_u24_e32 v133, 0x3ff, v133
	v_add_u32_e32 v135, v107, v133
	s_mov_b32 s60, 0xaaaaaaaa
	s_mov_b32 s61, 0xaaaaaaaa
	s_mov_b32 s62, 0xcccccccc
	s_mov_b32 s63, 0xcccccccc
	s_waitcnt lgkmcnt(0)
	s_branch .LBB0_2164
.LBB0_2163:
	s_add_i32 s17, s17, 4
	v_add_u32_e32 v135, 0x1000, v135
	v_add_u32_e32 v130, 0x400, v130
	s_cmp_gt_u32 s17, 29
	v_add_u32_e32 v129, 0x800, v129
	s_cbranch_scc1 .LBB0_2172
.LBB0_2164:
	ds_read_b128 v[34:37], v129
	ds_read_b128 v[30:33], v129 offset:256
	ds_read_b128 v[26:29], v129 offset:16384
	ds_read_b128 v[22:25], v129 offset:16640
	ds_read2_b32 v[80:81], v130 offset1:32
	s_waitcnt lgkmcnt(8)
	v_pk_fma_f32 v[70:71], v[20:21], v[70:71], v[78:79] op_sel_hi:[1,1,0]
	v_pk_fma_f32 v[76:77], v[20:21], v[76:77], v[78:79] op_sel:[0,0,1]
	v_pk_fma_f32 v[64:65], v[18:19], v[64:65], v[78:79] op_sel_hi:[1,1,0]
	v_pk_fma_f32 v[82:83], v[18:19], v[62:63], v[78:79] op_sel:[0,0,1]
	s_waitcnt lgkmcnt(7)
	v_pk_fma_f32 v[68:69], v[14:15], v[68:69], v[78:79] op_sel_hi:[1,1,0]
	v_pk_fma_f32 v[74:75], v[14:15], v[74:75], v[78:79] op_sel:[0,0,1]
	v_pk_fma_f32 v[66:67], v[16:17], v[66:67], v[78:79] op_sel_hi:[1,1,0]
	v_pk_fma_f32 v[72:73], v[16:17], v[72:73], v[78:79] op_sel:[0,0,1]
	v_pk_mul_f32 v[14:15], v[12:13], v[70:71]
	v_pk_mul_f32 v[12:13], v[12:13], v[76:77]
	v_pk_fma_f32 v[14:15], v[10:11], v[64:65], v[14:15]
	v_pk_fma_f32 v[10:11], v[10:11], v[82:83], v[12:13]
	v_pk_fma_f32 v[12:13], v[8:9], v[66:67], v[14:15]
	v_pk_fma_f32 v[8:9], v[8:9], v[72:73], v[10:11]
	v_pk_fma_f32 v[12:13], v[6:7], v[68:69], v[12:13]
	v_pk_fma_f32 v[6:7], v[6:7], v[74:75], v[8:9]
	v_add_f32_e32 v137, v12, v13
	v_add_f32_e32 v141, v6, v7
	s_waitcnt lgkmcnt(0)
	ds_read_b128 v[18:21], v129 offset:512
	ds_read_b128 v[14:17], v129 offset:768
	ds_read_b128 v[10:13], v129 offset:16896
	ds_read_b128 v[6:9], v129 offset:17152
	ds_read2_b32 v[62:63], v130 offset0:64 offset1:96
	v_pk_fma_f32 v[70:71], v[70:71], v[36:37], v[80:81] op_sel_hi:[1,1,0]
	v_pk_fma_f32 v[76:77], v[36:37], v[76:77], v[80:81] op_sel:[0,0,1]
	v_pk_fma_f32 v[64:65], v[64:65], v[34:35], v[80:81] op_sel_hi:[1,1,0]
	v_pk_fma_f32 v[78:79], v[34:35], v[82:83], v[80:81] op_sel:[0,0,1]
	v_pk_fma_f32 v[82:83], v[68:69], v[30:31], v[80:81] op_sel_hi:[1,1,0]
	v_pk_fma_f32 v[84:85], v[74:75], v[30:31], v[80:81] op_sel:[0,0,1]
	v_pk_fma_f32 v[86:87], v[66:67], v[32:33], v[80:81] op_sel_hi:[1,1,0]
	v_pk_fma_f32 v[88:89], v[72:73], v[32:33], v[80:81] op_sel:[0,0,1]
	v_pk_mul_f32 v[30:31], v[28:29], v[70:71]
	v_pk_mul_f32 v[28:29], v[28:29], v[76:77]
	v_pk_fma_f32 v[30:31], v[26:27], v[64:65], v[30:31]
	v_pk_fma_f32 v[26:27], v[26:27], v[78:79], v[28:29]
	v_pk_fma_f32 v[28:29], v[24:25], v[86:87], v[30:31]
	v_pk_fma_f32 v[24:25], v[24:25], v[88:89], v[26:27]
	v_pk_fma_f32 v[28:29], v[22:23], v[82:83], v[28:29]
	v_pk_fma_f32 v[22:23], v[22:23], v[84:85], v[24:25]
	v_add_f32_e32 v138, v28, v29
	v_add_f32_e32 v142, v22, v23
	s_waitcnt lgkmcnt(0)
	ds_read_b128 v[34:37], v129 offset:1024
	ds_read_b128 v[30:33], v129 offset:1280
	ds_read_b128 v[26:29], v129 offset:17408
	ds_read_b128 v[22:25], v129 offset:17664
	ds_read2_b32 v[66:67], v130 offset0:128 offset1:160
	v_pk_fma_f32 v[70:71], v[20:21], v[70:71], v[62:63] op_sel_hi:[1,1,0]
	v_pk_fma_f32 v[72:73], v[20:21], v[76:77], v[62:63] op_sel:[0,0,1]
	v_pk_fma_f32 v[64:65], v[18:19], v[64:65], v[62:63] op_sel_hi:[1,1,0]
	v_pk_fma_f32 v[68:69], v[18:19], v[78:79], v[62:63] op_sel:[0,0,1]
	v_pk_fma_f32 v[74:75], v[14:15], v[82:83], v[62:63] op_sel_hi:[1,1,0]
	v_pk_fma_f32 v[80:81], v[14:15], v[84:85], v[62:63] op_sel:[0,0,1]
	v_pk_fma_f32 v[82:83], v[16:17], v[86:87], v[62:63] op_sel_hi:[1,1,0]
	v_pk_fma_f32 v[84:85], v[16:17], v[88:89], v[62:63] op_sel:[0,0,1]
	v_pk_mul_f32 v[14:15], v[12:13], v[70:71]
	v_pk_mul_f32 v[12:13], v[12:13], v[72:73]
	v_pk_fma_f32 v[14:15], v[10:11], v[64:65], v[14:15]
	v_pk_fma_f32 v[10:11], v[10:11], v[68:69], v[12:13]
	v_pk_fma_f32 v[12:13], v[8:9], v[82:83], v[14:15]
	v_pk_fma_f32 v[8:9], v[8:9], v[84:85], v[10:11]
	v_pk_fma_f32 v[12:13], v[6:7], v[74:75], v[12:13]
	v_pk_fma_f32 v[6:7], v[6:7], v[80:81], v[8:9]
	v_add_f32_e32 v139, v12, v13
	v_add_f32_e32 v143, v6, v7
	s_waitcnt lgkmcnt(0)
	v_pk_fma_f32 v[70:71], v[70:71], v[36:37], v[66:67] op_sel_hi:[1,1,0]
	v_pk_fma_f32 v[76:77], v[36:37], v[72:73], v[66:67] op_sel:[0,0,1]
	v_pk_fma_f32 v[64:65], v[64:65], v[34:35], v[66:67] op_sel_hi:[1,1,0]
	v_pk_fma_f32 v[62:63], v[34:35], v[68:69], v[66:67] op_sel:[0,0,1]
	v_pk_fma_f32 v[68:69], v[74:75], v[30:31], v[66:67] op_sel_hi:[1,1,0]
	v_pk_fma_f32 v[74:75], v[80:81], v[30:31], v[66:67] op_sel:[0,0,1]
	v_pk_fma_f32 v[72:73], v[84:85], v[32:33], v[66:67] op_sel:[0,0,1]
	v_pk_fma_f32 v[66:67], v[82:83], v[32:33], v[66:67] op_sel_hi:[1,1,0]
	v_pk_mul_f32 v[30:31], v[28:29], v[70:71]
	v_pk_mul_f32 v[28:29], v[28:29], v[76:77]
	v_pk_fma_f32 v[30:31], v[26:27], v[64:65], v[30:31]
	v_pk_fma_f32 v[26:27], v[26:27], v[62:63], v[28:29]
	v_pk_fma_f32 v[28:29], v[24:25], v[66:67], v[30:31]
	v_pk_fma_f32 v[24:25], v[24:25], v[72:73], v[26:27]
	v_pk_fma_f32 v[28:29], v[22:23], v[68:69], v[28:29]
	v_pk_fma_f32 v[22:23], v[22:23], v[74:75], v[24:25]
	v_add_f32_e32 v140, v28, v29
	v_add_f32_e32 v144, v22, v23
	ds_read2_b32 v[78:79], v130 offset0:192 offset1:224
	ds_read_b128 v[18:21], v129 offset:1536
	ds_read_b128 v[14:17], v129 offset:1792
	ds_read_b128 v[10:13], v129 offset:17920
	ds_read_b128 v[6:9], v129 offset:18176
	v_cndmask_b32_e64 v145, v137, v138, s[60:61]
	v_cndmask_b32_e64 v146, v138, v137, s[60:61]
	v_cndmask_b32_e64 v147, v139, v140, s[60:61]
	v_cndmask_b32_e64 v148, v140, v139, s[60:61]
	v_cndmask_b32_e64 v149, v141, v142, s[60:61]
	v_cndmask_b32_e64 v150, v142, v141, s[60:61]
	v_cndmask_b32_e64 v151, v143, v144, s[60:61]
	v_cndmask_b32_e64 v152, v144, v143, s[60:61]
	v_add_f32_dpp v145, v146, v145 quad_perm:[1,0,3,2] row_mask:0xf bank_mask:0xf bound_ctrl:1
	v_add_f32_dpp v147, v148, v147 quad_perm:[1,0,3,2] row_mask:0xf bank_mask:0xf bound_ctrl:1
	v_add_f32_dpp v149, v150, v149 quad_perm:[1,0,3,2] row_mask:0xf bank_mask:0xf bound_ctrl:1
	v_add_f32_dpp v151, v152, v151 quad_perm:[1,0,3,2] row_mask:0xf bank_mask:0xf bound_ctrl:1
	v_cndmask_b32_e64 v146, v147, v145, s[62:63]
	v_cndmask_b32_e64 v148, v151, v149, s[62:63]
	v_cndmask_b32_e64 v133, v145, v147, s[62:63]
	v_cndmask_b32_e64 v134, v149, v151, s[62:63]
	v_add_f32_dpp v133, v146, v133 quad_perm:[2,3,0,1] row_mask:0xf bank_mask:0xf bound_ctrl:1
	v_add_f32_dpp v134, v148, v134 quad_perm:[2,3,0,1] row_mask:0xf bank_mask:0xf bound_ctrl:1
	ds_write_b32 v135, v133
	ds_write_b32 v135, v134 offset:512
	s_branch .LBB0_2163
